# P0 weight conversion split: idle workgroups of P1/P4/P10 tail rounds convert later-phase weights
# speedup vs baseline: 1.0035x; 1.0035x over previous
; #define LAS __attribute__((address_space(3)))
; __global__ void __launch_bounds__(NTHREADS, 2) fwd_kernel(Params P) {
;     ...
;     const XcdBarrier gbar = xcd_barrier_post((unsigned*)(P.ws + WS_BAR), bst);
;     ...
;     if (PHON(0)) {
;         LAS float* scr = (LAS float*)(lds + wave * 16384);
;         constexpr int IT_GU = (D / 64) * (NZ / 32), IT_DN = (FF / 64) * (D / 32), IT_SQ = (D / 64) * (D / 32), IT_BR = (BW / 64) * (D / 32), IT_LR = 2 * 4;
;         constexpr int IT_TOTAL = 3 * IT_GU + 2 * IT_DN + 2 * IT_SQ + 3 * IT_BR + 16 * IT_LR;
;         for (int it = gw; it < IT_TOTAL; it += NGW) {
;             int r = it; const float* W; bf16_t* WT; int N, ldk, mode = 0; const float* fg = nullptr; const float* fb = nullptr; float* cs = nullptr;
;             if (r < IT_GU) { W = P.in[I_WIN]; WT = WIN; N = NZ; ldk = D; fg = P.in[I_LN1G]; fb = P.in[I_LN1B]; cs = CSUM; }
;             else if ((r -= IT_GU) < IT_SQ) { W = P.in[I_WKV]; WT = WKV; N = D; ldk = D; }
;             else if ((r -= IT_SQ) < 3 * IT_BR) { const int k = r / IT_BR; r -= k * IT_BR; W = P.in[I_WBR] + (size_t)k * BW * D; WT = WBR + (size_t)k * D * BW; N = D; ldk = BW; }
;             else if ((r -= 3 * IT_BR) < IT_SQ) { W = P.in[I_WOUT]; WT = WOUT; N = D; ldk = D; }
;             else if ((r -= IT_SQ) < IT_GU) { W = P.in[I_GU2]; WT = WGU2; N = NZ; ldk = D; mode = 1; fg = P.in[I_LN2G]; fb = P.in[I_LN2B]; cs = CSUM + 2 * NZ; }
;             else if ((r -= IT_GU) < IT_DN) { W = P.in[I_DN2]; WT = WD2; N = D; ldk = FF; }
;             else if ((r -= IT_DN) < 16 * IT_LR) { const int m = r / IT_LR; r -= m * IT_LR; const int k = m >> 1, x = m & 1;
;                 W = (x ? P.in[I_LWX] : P.in[I_LWA]) + (size_t)k * 128 * 128; WT = WLRU + (size_t)k * 256 * 128 + x * 128 * 128; N = 128; ldk = 128; }
;             else if ((r -= 16 * IT_LR) < IT_DN) { W = P.in[I_DN1]; WT = WD1; N = D; ldk = FF; }
;             else { r -= IT_DN; W = P.in[I_GU1]; WT = WGU1; N = NZ; ldk = D; mode = 1; }
;             const int nblk = N / 32, kb = r / nblk, nb = r % nblk, n0 = 32 * nb;
;             int dr = n0;
;             if (mode == 1) dr = (n0 < FF) ? (n0 / 128) * 256 + (n0 % 128) : ((n0 - FF) / 128) * 256 + 128 + ((n0 - FF) % 128);
;             transpose_item(W, N, WT, ldk, 64 * kb, n0, dr, scr, lane, fg, fb, cs);
.LBB0_5:
	s_or_b64 exec, exec, s[4:5]
	s_load_dwordx16 s[8:23], s[0:1], 0x0
	s_lshl_b32 s86, s94, 3
	v_and_b32_e32 v237, 63, v178
	v_mbcnt_lo_u32_b32 v179, -1, 0
	s_waitcnt lgkmcnt(0)
	v_writelane_b32 v254, s8, 45
	s_nop 1
	v_writelane_b32 v254, s9, 46
	v_writelane_b32 v254, s10, 47
	v_writelane_b32 v254, s11, 48
	v_writelane_b32 v254, s12, 49
	v_writelane_b32 v254, s13, 50
	v_writelane_b32 v254, s14, 51
	v_writelane_b32 v254, s15, 52
	v_writelane_b32 v254, s16, 53
	v_writelane_b32 v254, s17, 54
	v_writelane_b32 v254, s18, 55
	v_writelane_b32 v254, s19, 56
	v_writelane_b32 v254, s20, 57
	v_writelane_b32 v254, s21, 58
	v_writelane_b32 v254, s22, 59
	v_writelane_b32 v254, s23, 60
	s_load_dwordx16 s[8:23], s[0:1], 0x80
	s_lshr_b32 s1, s37, 6
	s_lshl_b32 s0, s34, 3
	s_add_i32 s0, s1, s0
	s_mov_b32 s30, s0
	s_waitcnt lgkmcnt(0)
	v_writelane_b32 v254, s8, 61
	s_cmp_gt_i32 s0, 0xcc7f
	s_nop 0
	v_writelane_b32 v255, s11, 0
	v_writelane_b32 v255, s12, 1
	v_writelane_b32 v255, s13, 2
	v_writelane_b32 v255, s14, 3
	v_writelane_b32 v255, s15, 4
	v_writelane_b32 v255, s16, 5
	v_writelane_b32 v255, s17, 6
	v_writelane_b32 v255, s18, 7
	v_writelane_b32 v255, s19, 8
	v_writelane_b32 v255, s20, 9
	v_writelane_b32 v255, s21, 10
	v_writelane_b32 v255, s22, 11
	v_writelane_b32 v254, s9, 62
	v_writelane_b32 v255, s23, 12
	v_writelane_b32 v254, s10, 63
	v_writelane_b32 v255, s1, 13
	s_cbranch_scc1 .LBB0_62
	s_mov_b32 s100, 0
	s_movk_i32 s98, 0x2bff
.Lcv_entry:
	v_readlane_b32 s0, v255, 13
	s_lshl_b32 s0, s0, 14
	s_add_i32 s2, s0, 0
	s_add_u32 s38, s92, 0x2c00000
	s_addc_u32 s39, s93, 0
	s_add_u32 s49, s92, 0xcc00000
	s_addc_u32 s50, s93, 0
	s_add_u32 s12, s92, 0xb600000
	s_addc_u32 s13, s93, 0
	s_add_u32 s14, s92, 0x8a00000
	s_addc_u32 s15, s93, 0
	s_add_u32 s16, s92, 0x2b1b9600
	s_addc_u32 s17, s93, 0
	s_add_u32 s18, s92, 0x8200000
	s_addc_u32 s19, s93, 0
	s_add_u32 s31, s92, 0x7600000
	s_addc_u32 s33, s93, 0
	s_add_u32 s20, s92, 0x6e00000
	s_addc_u32 s21, s93, 0
	s_add_u32 s22, s92, 0x4200000
	v_and_b32_e32 v3, 7, v178
	v_lshrrev_b32_e32 v22, 3, v237
	s_addc_u32 s23, s93, 0
	v_lshl_add_u32 v4, v3, 4, s2
	v_mul_u32_u24_e32 v5, 0x84, v22
	s_add_u32 s24, s92, 0x2b1a3600
	v_lshlrev_b32_e32 v2, 2, v3
	v_mov_b32_e32 v25, 0
	v_lshlrev_b32_e32 v26, 3, v3
	v_mul_u32_u24_e32 v6, 0x420, v3
	v_cmp_eq_u32_e64 s[0:1], 0, v3
	v_lshlrev_b32_e32 v3, 2, v22
	v_add_u32_e32 v41, v4, v5
	s_mov_b32 s9, 0
	s_addc_u32 s25, s93, 0
	v_or_b32_e32 v1, 8, v22
	v_or_b32_e32 v23, 16, v22
	v_or_b32_e32 v27, 24, v22
	v_add3_u32 v40, s2, v6, v3
	s_bfe_u32 s35, s37, 0x30006
	v_lshlrev_b32_e32 v28, 2, v2
	v_mov_b32_e32 v29, v25
	v_add_u32_e32 v42, 0x420, v41
	v_add_u32_e32 v43, 0x428, v41
	v_add_u32_e32 v44, 0x840, v41
	v_add_u32_e32 v45, 0x848, v41
	v_add_u32_e32 v46, 0xc60, v41
	v_add_u32_e32 v47, 0xc68, v41
	v_add_u32_e32 v48, 0x1080, v41
	v_add_u32_e32 v49, 0x1088, v41
	v_add_u32_e32 v50, 0x14a0, v41
	v_add_u32_e32 v51, 0x14a8, v41
	v_add_u32_e32 v52, 0x18c0, v41
	v_add_u32_e32 v53, 0x18c8, v41
	v_add_u32_e32 v54, 0x1ce0, v41
	v_add_u32_e32 v55, 0x1ce8, v41
	v_lshlrev_b32_e32 v24, 1, v26
	v_mbcnt_hi_u32_b32 v56, -1, v179
	s_mov_b32 s2, s30
	s_mov_b32 s36, s86
	s_branch .LBB0_9

; __global__ void __launch_bounds__(NTHREADS, 2) fwd_kernel(Params P) {
;     ...
;         for (int it = gw; it < IT_TOTAL; it += NGW) {
.LBB0_8:
	s_waitcnt lgkmcnt(0)
	s_add_i32 s2, s2, s36
	s_mov_b32 s86, s36
	s_cmp_gt_i32 s2, s98
	s_cbranch_scc1 .Lcv_exit

; __global__ void __launch_bounds__(NTHREADS, 2) fwd_kernel(Params P) {
;     ...
;         constexpr int IT_GU = (D / 64) * (NZ / 32), IT_DN = (FF / 64) * (D / 32), IT_SQ = (D / 64) * (D / 32), IT_BR = (BW / 64) * (D / 32), IT_LR = 2 * 4;
;         constexpr int IT_TOTAL = 3 * IT_GU + 2 * IT_DN + 2 * IT_SQ + 3 * IT_BR + 16 * IT_LR;
;         for (int it = gw; it < IT_TOTAL; it += NGW) {
.Lcv_exit:
	s_cmp_lg_u32 s100, 0
	s_cbranch_scc1 .Lcv_d1
	s_mov_b32 s100, 1
	s_movk_i32 s98, 0x73ff
	v_readlane_b32 s99, v255, 13
	s_lshl_b32 s101, s34, 3
	s_nop 3
	s_add_i32 s99, s99, s101
	s_add_i32 s30, s99, 0x400
	s_and_b32 s30, s30, 0x7ff
	s_add_i32 s30, s30, 0x5800
	s_branch .Lcv_entry
.Lcv_d1:
	s_cmp_lg_u32 s100, 1
	s_cbranch_scc1 .Lcv_d2
	s_mov_b32 s100, 2
	s_mov_b32 s98, 0xcc7f
	v_readlane_b32 s99, v255, 13
	s_lshl_b32 s101, s34, 3
	s_nop 3
	s_add_i32 s99, s99, s101
	s_add_i32 s30, s99, 0x8a00
	s_branch .Lcv_entry
.Lcv_d2:
	s_cmp_lg_u32 s100, 2
	s_cbranch_scc1 .Lcv_d3
	v_readlane_b32 s99, v255, 13
	s_lshl_b32 s101, s34, 3
	s_nop 3
	s_add_i32 s99, s99, s101
	s_mov_b32 s30, s99
	s_branch .LBB0_62
.Lcv_d3:
	s_cmp_lg_u32 s100, 3
	s_cbranch_scc0 .Lcv_ret_p1
	s_cmp_lg_u32 s100, 4
	s_cbranch_scc0 .Lcv_ret_p4
	s_branch .Lcv_hop_ret_p10

; __global__ void __launch_bounds__(NTHREADS, 2) fwd_kernel(Params P) {
;     ...
;     if (PHON(1)) {
;         pg8::PlainSched S{XB, WGU1, 33, 44, D, D, G, bid};
;         pg8::EpiSwiglu E{H, FF, nullptr, nullptr};
;         pg8::gemm_phase<pg8::PlainSched, pg8::EpiSwiglu, true, true>(lds, D, D, D, S, E);
;     }
.LBB0_162:
	s_cmp_lt_u32 s34, 172
	s_cbranch_scc1 .Lcv_skip_p1
	v_writelane_b32 v252, s0, 0
	v_writelane_b32 v252, s1, 1
	v_writelane_b32 v252, s2, 2
	v_writelane_b32 v252, s3, 3
	v_writelane_b32 v252, s4, 4
	v_writelane_b32 v252, s5, 5
	v_writelane_b32 v252, s6, 6
	v_writelane_b32 v252, s7, 7
	v_writelane_b32 v252, s8, 8
	v_writelane_b32 v252, s9, 9
	v_writelane_b32 v252, s10, 10
	v_writelane_b32 v252, s11, 11
	v_writelane_b32 v252, s12, 12
	v_writelane_b32 v252, s13, 13
	v_writelane_b32 v252, s14, 14
	v_writelane_b32 v252, s15, 15
	v_writelane_b32 v252, s16, 16
	v_writelane_b32 v252, s17, 17
	v_writelane_b32 v252, s18, 18
	v_writelane_b32 v252, s19, 19
	v_writelane_b32 v252, s20, 20
	v_writelane_b32 v252, s21, 21
	v_writelane_b32 v252, s22, 22
	v_writelane_b32 v252, s23, 23
	v_writelane_b32 v252, s24, 24
	v_writelane_b32 v252, s25, 25
	v_writelane_b32 v252, s26, 26
	v_writelane_b32 v252, s27, 27
	v_writelane_b32 v252, s28, 28
	v_writelane_b32 v252, s29, 29
	v_writelane_b32 v252, s30, 30
	v_writelane_b32 v252, s31, 31
	v_writelane_b32 v252, s32, 32
	v_writelane_b32 v252, s33, 33
	v_writelane_b32 v252, s34, 34
	v_writelane_b32 v252, s35, 35
	v_writelane_b32 v252, s36, 36
	v_writelane_b32 v252, s37, 37
	v_writelane_b32 v252, s38, 38
	v_writelane_b32 v252, s39, 39
	v_writelane_b32 v252, s40, 40
	v_writelane_b32 v252, s41, 41
	v_writelane_b32 v252, s42, 42
	v_writelane_b32 v252, s43, 43
	v_writelane_b32 v252, s44, 44
	v_writelane_b32 v252, s45, 45
	v_writelane_b32 v252, s46, 46
	v_writelane_b32 v252, s47, 47
	v_writelane_b32 v252, s48, 48
	v_writelane_b32 v252, s49, 49
	v_writelane_b32 v252, s50, 50
	v_writelane_b32 v252, s51, 51
	v_writelane_b32 v252, s52, 52
	v_writelane_b32 v252, s53, 53
	v_writelane_b32 v252, s54, 54
	v_writelane_b32 v252, s55, 55
	v_writelane_b32 v252, s56, 56
	v_writelane_b32 v252, s57, 57
	v_writelane_b32 v252, s58, 58
	v_writelane_b32 v252, s59, 59
	v_writelane_b32 v252, s60, 60
	v_writelane_b32 v252, s61, 61
	v_writelane_b32 v252, s62, 62
	v_writelane_b32 v252, s63, 63
	v_writelane_b32 v253, s64, 0
	v_writelane_b32 v253, s65, 1
	v_writelane_b32 v253, s66, 2
	v_writelane_b32 v253, s67, 3
	v_writelane_b32 v253, s68, 4
	v_writelane_b32 v253, s69, 5
	v_writelane_b32 v253, s70, 6
	v_writelane_b32 v253, s71, 7
	v_writelane_b32 v253, s72, 8
	v_writelane_b32 v253, s73, 9
	v_writelane_b32 v253, s74, 10
	v_writelane_b32 v253, s75, 11
	v_writelane_b32 v253, s76, 12
	v_writelane_b32 v253, s77, 13
	v_writelane_b32 v253, s78, 14
	v_writelane_b32 v253, s79, 15
	v_writelane_b32 v253, s80, 16
	v_writelane_b32 v253, s81, 17
	v_writelane_b32 v253, s82, 18
	v_writelane_b32 v253, s83, 19
	v_writelane_b32 v253, s84, 20
	v_writelane_b32 v253, s85, 21
	v_writelane_b32 v253, s86, 22
	v_writelane_b32 v253, s87, 23
	v_writelane_b32 v253, s88, 24
	v_writelane_b32 v253, s89, 25
	v_writelane_b32 v253, s90, 26
	v_writelane_b32 v253, s91, 27
	v_writelane_b32 v253, s92, 28
	v_writelane_b32 v253, s93, 29
	v_writelane_b32 v253, s94, 30
	v_writelane_b32 v253, s95, 31
	v_writelane_b32 v253, s96, 32
	v_writelane_b32 v253, s97, 33
	s_mov_b32 s100, 3
	s_mov_b32 s98, 0x47ff
	v_and_b32_e32 v237, 63, v178
	v_readlane_b32 s99, v255, 13
	v_readfirstlane_b32 s37, v178
	s_nop 4
	s_sub_i32 s101, s34, 172
	s_lshl_b32 s101, s101, 3
	s_add_i32 s99, s99, s101
	s_add_i32 s30, s99, 0x2c00
	s_movk_i32 s86, 672
	s_branch .Lcv_entry
.Lcv_ret_p1:
	v_readlane_b32 s0, v252, 0
	v_readlane_b32 s1, v252, 1
	v_readlane_b32 s2, v252, 2
	v_readlane_b32 s3, v252, 3
	v_readlane_b32 s4, v252, 4
	v_readlane_b32 s5, v252, 5
	v_readlane_b32 s6, v252, 6
	v_readlane_b32 s7, v252, 7
	v_readlane_b32 s8, v252, 8
	v_readlane_b32 s9, v252, 9
	v_readlane_b32 s10, v252, 10
	v_readlane_b32 s11, v252, 11
	v_readlane_b32 s12, v252, 12
	v_readlane_b32 s13, v252, 13
	v_readlane_b32 s14, v252, 14
	v_readlane_b32 s15, v252, 15
	v_readlane_b32 s16, v252, 16
	v_readlane_b32 s17, v252, 17
	v_readlane_b32 s18, v252, 18
	v_readlane_b32 s19, v252, 19
	v_readlane_b32 s20, v252, 20
	v_readlane_b32 s21, v252, 21
	v_readlane_b32 s22, v252, 22
	v_readlane_b32 s23, v252, 23
	v_readlane_b32 s24, v252, 24
	v_readlane_b32 s25, v252, 25
	v_readlane_b32 s26, v252, 26
	v_readlane_b32 s27, v252, 27
	v_readlane_b32 s28, v252, 28
	v_readlane_b32 s29, v252, 29
	v_readlane_b32 s30, v252, 30
	v_readlane_b32 s31, v252, 31
	v_readlane_b32 s32, v252, 32
	v_readlane_b32 s33, v252, 33
	v_readlane_b32 s34, v252, 34
	v_readlane_b32 s35, v252, 35
	v_readlane_b32 s36, v252, 36
	v_readlane_b32 s37, v252, 37
	v_readlane_b32 s38, v252, 38
	v_readlane_b32 s39, v252, 39
	v_readlane_b32 s40, v252, 40
	v_readlane_b32 s41, v252, 41
	v_readlane_b32 s42, v252, 42
	v_readlane_b32 s43, v252, 43
	v_readlane_b32 s44, v252, 44
	v_readlane_b32 s45, v252, 45
	v_readlane_b32 s46, v252, 46
	v_readlane_b32 s47, v252, 47
	v_readlane_b32 s48, v252, 48
	v_readlane_b32 s49, v252, 49
	v_readlane_b32 s50, v252, 50
	v_readlane_b32 s51, v252, 51
	v_readlane_b32 s52, v252, 52
	v_readlane_b32 s53, v252, 53
	v_readlane_b32 s54, v252, 54
	v_readlane_b32 s55, v252, 55
	v_readlane_b32 s56, v252, 56
	v_readlane_b32 s57, v252, 57
	v_readlane_b32 s58, v252, 58
	v_readlane_b32 s59, v252, 59
	v_readlane_b32 s60, v252, 60
	v_readlane_b32 s61, v252, 61
	v_readlane_b32 s62, v252, 62
	v_readlane_b32 s63, v252, 63
	v_readlane_b32 s64, v253, 0
	v_readlane_b32 s65, v253, 1
	v_readlane_b32 s66, v253, 2
	v_readlane_b32 s67, v253, 3
	v_readlane_b32 s68, v253, 4
	v_readlane_b32 s69, v253, 5
	v_readlane_b32 s70, v253, 6
	v_readlane_b32 s71, v253, 7
	v_readlane_b32 s72, v253, 8
	v_readlane_b32 s73, v253, 9
	v_readlane_b32 s74, v253, 10
	v_readlane_b32 s75, v253, 11
	v_readlane_b32 s76, v253, 12
	v_readlane_b32 s77, v253, 13
	v_readlane_b32 s78, v253, 14
	v_readlane_b32 s79, v253, 15
	v_readlane_b32 s80, v253, 16
	v_readlane_b32 s81, v253, 17
	v_readlane_b32 s82, v253, 18
	v_readlane_b32 s83, v253, 19
	v_readlane_b32 s84, v253, 20
	v_readlane_b32 s85, v253, 21
	v_readlane_b32 s86, v253, 22
	v_readlane_b32 s87, v253, 23
	v_readlane_b32 s88, v253, 24
	v_readlane_b32 s89, v253, 25
	v_readlane_b32 s90, v253, 26
	v_readlane_b32 s91, v253, 27
	v_readlane_b32 s92, v253, 28
	v_readlane_b32 s93, v253, 29
	v_readlane_b32 s94, v253, 30
	v_readlane_b32 s95, v253, 31
	v_readlane_b32 s96, v253, 32
	v_readlane_b32 s97, v253, 33
	s_nop 4

; #define LAS __attribute__((address_space(3)))
; __global__ void __launch_bounds__(NTHREADS, 2) fwd_kernel(Params P) {
;     ...
;     if (PHON(4)) {
;         LAS float* gbl = (LAS float*)(lds + 131072);
;         for (int i = tid; i < 3 * D / 4; i += NTHREADS) *(LAS f32x4*)(gbl + 4 * i) = *(const f32x4*)(P.in[I_GATEB] + 4 * i);
;         __syncthreads();
;         pg8::WinSched S{XB, WIN, MEMLN, WKV, G, bid};
;         pg8::EpiWin E{Z, gbl, out + O_MK, out + O_MV, KB, VT, RSUM, CSUM};
;         pg8::gemm_phase<pg8::WinSched, pg8::EpiWin, true, true>(lds, D, D, D, S, E);
;     }
.LBB0_506:
	s_cmp_lt_u32 s34, 220
	s_cbranch_scc1 .Lcv_skip_p4
	v_writelane_b32 v252, s0, 0
	v_writelane_b32 v252, s1, 1
	v_writelane_b32 v252, s2, 2
	v_writelane_b32 v252, s3, 3
	v_writelane_b32 v252, s4, 4
	v_writelane_b32 v252, s5, 5
	v_writelane_b32 v252, s6, 6
	v_writelane_b32 v252, s7, 7
	v_writelane_b32 v252, s8, 8
	v_writelane_b32 v252, s9, 9
	v_writelane_b32 v252, s10, 10
	v_writelane_b32 v252, s11, 11
	v_writelane_b32 v252, s12, 12
	v_writelane_b32 v252, s13, 13
	v_writelane_b32 v252, s14, 14
	v_writelane_b32 v252, s15, 15
	v_writelane_b32 v252, s16, 16
	v_writelane_b32 v252, s17, 17
	v_writelane_b32 v252, s18, 18
	v_writelane_b32 v252, s19, 19
	v_writelane_b32 v252, s20, 20
	v_writelane_b32 v252, s21, 21
	v_writelane_b32 v252, s22, 22
	v_writelane_b32 v252, s23, 23
	v_writelane_b32 v252, s24, 24
	v_writelane_b32 v252, s25, 25
	v_writelane_b32 v252, s26, 26
	v_writelane_b32 v252, s27, 27
	v_writelane_b32 v252, s28, 28
	v_writelane_b32 v252, s29, 29
	v_writelane_b32 v252, s30, 30
	v_writelane_b32 v252, s31, 31
	v_writelane_b32 v252, s32, 32
	v_writelane_b32 v252, s33, 33
	v_writelane_b32 v252, s34, 34
	v_writelane_b32 v252, s35, 35
	v_writelane_b32 v252, s36, 36
	v_writelane_b32 v252, s37, 37
	v_writelane_b32 v252, s38, 38
	v_writelane_b32 v252, s39, 39
	v_writelane_b32 v252, s40, 40
	v_writelane_b32 v252, s41, 41
	v_writelane_b32 v252, s42, 42
	v_writelane_b32 v252, s43, 43
	v_writelane_b32 v252, s44, 44
	v_writelane_b32 v252, s45, 45
	v_writelane_b32 v252, s46, 46
	v_writelane_b32 v252, s47, 47
	v_writelane_b32 v252, s48, 48
	v_writelane_b32 v252, s49, 49
	v_writelane_b32 v252, s50, 50
	v_writelane_b32 v252, s51, 51
	v_writelane_b32 v252, s52, 52
	v_writelane_b32 v252, s53, 53
	v_writelane_b32 v252, s54, 54
	v_writelane_b32 v252, s55, 55
	v_writelane_b32 v252, s56, 56
	v_writelane_b32 v252, s57, 57
	v_writelane_b32 v252, s58, 58
	v_writelane_b32 v252, s59, 59
	v_writelane_b32 v252, s60, 60
	v_writelane_b32 v252, s61, 61
	v_writelane_b32 v252, s62, 62
	v_writelane_b32 v252, s63, 63
	v_writelane_b32 v253, s64, 0
	v_writelane_b32 v253, s65, 1
	v_writelane_b32 v253, s66, 2
	v_writelane_b32 v253, s67, 3
	v_writelane_b32 v253, s68, 4
	v_writelane_b32 v253, s69, 5
	v_writelane_b32 v253, s70, 6
	v_writelane_b32 v253, s71, 7
	v_writelane_b32 v253, s72, 8
	v_writelane_b32 v253, s73, 9
	v_writelane_b32 v253, s74, 10
	v_writelane_b32 v253, s75, 11
	v_writelane_b32 v253, s76, 12
	v_writelane_b32 v253, s77, 13
	v_writelane_b32 v253, s78, 14
	v_writelane_b32 v253, s79, 15
	v_writelane_b32 v253, s80, 16
	v_writelane_b32 v253, s81, 17
	v_writelane_b32 v253, s82, 18
	v_writelane_b32 v253, s83, 19
	v_writelane_b32 v253, s84, 20
	v_writelane_b32 v253, s85, 21
	v_writelane_b32 v253, s86, 22
	v_writelane_b32 v253, s87, 23
	v_writelane_b32 v253, s88, 24
	v_writelane_b32 v253, s89, 25
	v_writelane_b32 v253, s90, 26
	v_writelane_b32 v253, s91, 27
	v_writelane_b32 v253, s92, 28
	v_writelane_b32 v253, s93, 29
	v_writelane_b32 v253, s94, 30
	v_writelane_b32 v253, s95, 31
	v_writelane_b32 v253, s96, 32
	v_writelane_b32 v253, s97, 33
	s_mov_b32 s100, 4
	s_mov_b32 s98, 0x57ff
	v_and_b32_e32 v237, 63, v178
	v_readlane_b32 s99, v255, 13
	v_readfirstlane_b32 s37, v178
	s_nop 4
	s_sub_i32 s101, s34, 220
	s_lshl_b32 s101, s101, 3
	s_add_i32 s99, s99, s101
	s_add_i32 s30, s99, 0x4800
	s_movk_i32 s86, 288
	s_branch .Lcv_entry

; #define LAS __attribute__((address_space(3)))
; __global__ void __launch_bounds__(NTHREADS, 2) fwd_kernel(Params P) {
;     ...
;                     if (seg == 3) { SUM[(size_t)(c * 2 + 0) * BW + ch0 + chn] = pa * cA; SUM[(size_t)(c * 2 + 1) * BW + ch0 + chn] = h + pa * cH; }
;     ...
;     if (PHON(7)) for (int it = bid; it < 256; it += G) {
;         const int b = it >> 6, h = (it >> 4) & 3, qt = it & 15;
;         int lane_o = lane; asm volatile("" : "+v"(lane_o));
;         const int fr = lane_o & 15, fq = lane_o >> 4;
;         const int row0 = b * SEQ + qt * 128 + wave * 16;
;         bf16x8 qf[8];
; #pragma unroll
;         for (int ks = 0; ks < 8; ++ks) qf[ks] = *(const bf16x8*)(Z + (size_t)(row0 + fr) * NZ + 4096 + h * HD + ks * 32 + fq * 8);
;         f32x4 s[16];
;         LAS bf16_t* KL = (LAS bf16_t*)lds;
;         __syncthreads();
;         {
;             const bf16_t* kb = KB + (size_t)(b * NMEM) * 1024 + h * HD;
;             u32x4 t[16];
; #pragma unroll
;             for (int i = 0; i < 16; ++i) { const int e = tid + i * NTHREADS, m = e >> 5, c8 = (e & 31) * 8; t[i] = *(const u32x4*)(kb + (size_t)m * 1024 + c8); }
; #pragma unroll
;             for (int i = 0; i < 16; ++i) { const int e = tid + i * NTHREADS, m = e >> 5, c8 = (e & 31) * 8; *(LAS u32x4*)(KL + m * 264 + c8) = t[i]; }
;         }
;         asm volatile("" ::: "memory");
;         u32x4 tv[16];
;         {
;             const bf16_t* vt0 = VT + (size_t)(h * HD) * 1024 + b * NMEM;
; #pragma unroll
;             for (int i = 0; i < 16; ++i) { const int e = tid + i * NTHREADS, dd = e >> 5, c8 = (e & 31) * 8; tv[i] = *(const u32x4*)(vt0 + (size_t)dd * 1024 + c8); }
.LBB0_624:
	s_or_b64 exec, exec, s[0:1]
	s_and_saveexec_b64 s[0:1], s[22:23]
	s_cbranch_execz .LBB0_579
	s_lshl_b32 s10, s9, 1
	s_ashr_i32 s11, s10, 31
	s_lshl_b64 s[24:25], s[10:11], 12
	s_add_u32 s9, s30, s24
	s_addc_u32 s11, s31, s25
	s_lshl_b32 s78, s8, 2
	s_add_u32 s24, s9, s78
	s_addc_u32 s25, s11, 0
	s_or_b32 s10, s10, 1
	s_ashr_i32 s11, s10, 31
	s_lshl_b64 s[10:11], s[10:11], 12
	s_add_u32 s9, s30, s10
	s_addc_u32 s11, s31, s11
	s_add_u32 s10, s9, s78
	v_mul_f32_e32 v33, v37, v34
	v_fmac_f32_e32 v36, v37, v32
	s_addc_u32 s11, s11, 0
	global_store_dword v194, v33, s[24:25]
	global_store_dword v194, v36, s[10:11]
	s_branch .LBB0_579
.Lcv_hop_entry:
	s_branch .Lcv_entry
.Lcv_hop_ret_p10:
	s_branch .Lcv_ret_p10
.LBB0_626:
	v_readlane_b32 s0, v255, 20
	v_readlane_b32 s1, v255, 21
	s_and_b64 vcc, exec, s[0:1]
	s_cbranch_vccnz .LBB0_631
	v_lshlrev_b32_e32 v1, 5, v178
	v_add_u32_e32 v5, 0xc000, v1
	v_and_b32_e32 v8, 0x1fc00, v5
	v_add_u32_e32 v5, 0x14000, v1
	v_and_b32_e32 v12, 0x1fc00, v5
	v_add_u32_e32 v5, 0x1c000, v1
	v_and_b32_e32 v16, 0x3fc00, v5
	v_add_u32_e32 v5, 0x24000, v1
	v_and_b32_e32 v20, 0x2fc00, v5
	v_add_u32_e32 v5, 0x2c000, v1
	v_lshlrev_b32_e32 v0, 3, v178
	v_and_b32_e32 v2, 0x7c00, v1
	v_add_u32_e32 v4, 0x4000, v1
	v_and_b32_e32 v24, 0x3fc00, v5
	v_add_u32_e32 v5, 0x34000, v1
	v_add_u32_e32 v1, 0x3c000, v1
	v_readlane_b32 s0, v255, 13
	v_and_b32_e32 v0, 0xf8, v0
	v_and_b32_e32 v28, 0x3fc00, v5
	v_and_b32_e32 v32, 0x7fc00, v1
	v_add_u32_e32 v1, 0x200, v178
	v_add_u32_e32 v5, 0x600, v178
	v_add_u32_e32 v7, 0xa00, v178
	v_add_u32_e32 v9, 0xe00, v178
	v_add_u32_e32 v11, 0x1200, v178
	v_add_u32_e32 v13, 0x1600, v178
	v_add_u32_e32 v15, 0x1a00, v178
	v_add_u32_e32 v17, 0x1e00, v178
	s_lshl_b32 s2, s0, 4
	v_lshl_add_u32 v3, v0, 1, 0
	s_movk_i32 s0, 0x210
	v_lshrrev_b32_e32 v1, 5, v1
	v_lshrrev_b32_e32 v5, 5, v5
	v_lshrrev_b32_e32 v7, 5, v7
	v_lshrrev_b32_e32 v9, 5, v9
	v_lshrrev_b32_e32 v11, 5, v11
	v_lshrrev_b32_e32 v13, 5, v13
	v_lshrrev_b32_e32 v15, 5, v15
	v_lshrrev_b32_e32 v17, 5, v17
	v_mbcnt_hi_u32_b32 v214, -1, v179
	v_mov_b32_e32 v157, 0
	v_and_b32_e32 v4, 0xfc00, v4
	v_or_b32_e32 v6, 0x8000, v2
	v_or_b32_e32 v10, 0x10000, v2
	v_or_b32_e32 v14, 0x18000, v2
	v_or_b32_e32 v18, 0x20000, v2
	v_or_b32_e32 v22, 0x28000, v2
	v_or_b32_e32 v26, 0x30000, v2
	v_or_b32_e32 v30, 0x38000, v2
	v_mad_u32_u24 v181, v177, s0, v3
	v_mul_u32_u24_e32 v1, 0x210, v1
	v_mul_u32_u24_e32 v5, 0x210, v5
	v_mul_u32_u24_e32 v7, 0x210, v7
	v_mul_u32_u24_e32 v9, 0x210, v9
	v_mul_u32_u24_e32 v11, 0x210, v11
	v_mul_u32_u24_e32 v13, 0x210, v13
	v_mul_u32_u24_e32 v15, 0x210, v15
	v_mul_u32_u24_e32 v17, 0x210, v17
	s_add_u32 s4, s92, 0x27821040
	v_lshlrev_b32_e32 v158, 1, v0
	v_and_b32_e32 v0, 64, v214
	s_mov_b32 s1, 0
	v_add_u32_e32 v202, 0x10800, v181
	v_add_u32_e32 v203, 0x14a00, v181
	v_add_u32_e32 v204, 0x18c00, v181
	v_add_u32_e32 v205, 0x1ce00, v181
	s_addc_u32 s5, s93, 0
	s_lshl_b32 s3, s34, 7
	s_lshl_b32 s10, s94, 7
	s_lshl_b32 s11, s34, 4
	s_lshl_b32 s12, s94, 4
	s_movk_i32 s13, 0x5800
	s_mov_b64 s[6:7], 0xeda2000
	s_mov_b32 s14, 0xeda2000
	v_lshlrev_b32_e32 v160, 1, v2
	v_lshlrev_b32_e32 v162, 1, v4
	v_lshlrev_b32_e32 v164, 1, v6
	v_lshlrev_b32_e32 v166, 1, v8
	v_lshlrev_b32_e32 v168, 1, v10
	v_lshlrev_b32_e32 v170, 1, v12
	v_lshlrev_b32_e32 v156, 1, v14
	v_lshlrev_b32_e32 v172, 1, v16
	v_mov_b32_e32 v173, v157
	v_lshlrev_b32_e32 v174, 1, v18
	v_mov_b32_e32 v175, v157
	v_lshlrev_b32_e32 v184, 1, v20
	v_mov_b32_e32 v185, v157
	v_lshlrev_b32_e32 v186, 1, v22
	v_mov_b32_e32 v187, v157
	v_lshlrev_b32_e32 v188, 1, v24
	v_mov_b32_e32 v189, v157
	v_lshlrev_b32_e32 v190, 1, v26
	v_mov_b32_e32 v191, v157
	v_lshlrev_b32_e32 v192, 1, v28
	v_mov_b32_e32 v193, v157
	v_lshlrev_b32_e32 v194, 1, v30
	v_mov_b32_e32 v195, v157
	v_lshlrev_b32_e32 v196, 1, v32
	v_mov_b32_e32 v197, v157
	v_add_u32_e32 v206, v3, v1
	v_add_u32_e32 v207, v3, v5
	v_add_u32_e32 v208, v3, v7
	v_add_u32_e32 v209, v3, v9
	v_add_u32_e32 v210, v3, v11
	v_add_u32_e32 v211, v3, v13
	v_add_u32_e32 v212, v3, v15
	v_add_u32_e32 v213, v3, v17
	s_mov_b32 s15, 0xff61b1e6
	s_movk_i32 s16, 0x1800
	s_mov_b64 s[8:9], 0x80
	v_mov_b64_e32 v[198:199], s[92:93]
	v_mov_b32_e32 v159, v157
	v_mov_b32_e32 v161, v157
	v_mov_b32_e32 v163, v157
	v_mov_b32_e32 v165, v157
	v_mov_b32_e32 v167, v157
	v_mov_b32_e32 v169, v157
	v_mov_b32_e32 v171, v157
	v_xor_b32_e32 v215, 16, v214
	v_add_u32_e32 v216, 64, v0
	v_xor_b32_e32 v217, 32, v214
	s_mov_b32 s17, s34

; #define LAS __attribute__((address_space(3)))
; __device__ __forceinline__ unsigned cvt_pk_bf16(float lo, float hi) { unsigned r; asm volatile("v_cvt_pk_bf16_f32 %0, %1, %2" : "=v"(r) : "v"(lo), "v"(hi)); return r; }
; __device__ __forceinline__ float bflo(unsigned w) { return __uint_as_float(w << 16); }
; __device__ __forceinline__ float bfhi(unsigned w) { return __uint_as_float(w & 0xffff0000u); }
; __global__ void __launch_bounds__(NTHREADS, 2) fwd_kernel(Params P) {
;     ...
;     if (PHON(10)) {
;         LAS bf16_t* VL = (LAS bf16_t*)lds;
;         for (int e = bid * NTHREADS + tid; e < MS * BW / 2; e += G * NTHREADS) {
;             const int r = e / (BW / 2), c2 = (e % (BW / 2)) * 2, g = c2 >> 8;
;             const float w00 = P.in[I_WS][(size_t)g * 128 * 128], b0 = P.in[I_BS][g * 128];
;             const unsigned vw = *(const unsigned*)(VP + (size_t)(MP + r) * BW + c2), uw = *(const unsigned*)(Z + (size_t)(MP + r) * NZ + c2);
;             *(unsigned*)(YS + (size_t)(MP + r) * 3072 + c2) = cvt_pk_bf16(bflo(uw) * (w00 * bflo(vw) + b0), bfhi(uw) * (w00 * bfhi(vw) + b0));
;         }
.LBB0_1044:
	s_cmp_lt_u32 s34, 172
	s_cbranch_scc1 .Lcv_skip_p10
	v_writelane_b32 v252, s0, 0
	v_writelane_b32 v252, s1, 1
	v_writelane_b32 v252, s2, 2
	v_writelane_b32 v252, s3, 3
	v_writelane_b32 v252, s4, 4
	v_writelane_b32 v252, s5, 5
	v_writelane_b32 v252, s6, 6
	v_writelane_b32 v252, s7, 7
	v_writelane_b32 v252, s8, 8
	v_writelane_b32 v252, s9, 9
	v_writelane_b32 v252, s10, 10
	v_writelane_b32 v252, s11, 11
	v_writelane_b32 v252, s12, 12
	v_writelane_b32 v252, s13, 13
	v_writelane_b32 v252, s14, 14
	v_writelane_b32 v252, s15, 15
	v_writelane_b32 v252, s16, 16
	v_writelane_b32 v252, s17, 17
	v_writelane_b32 v252, s18, 18
	v_writelane_b32 v252, s19, 19
	v_writelane_b32 v252, s20, 20
	v_writelane_b32 v252, s21, 21
	v_writelane_b32 v252, s22, 22
	v_writelane_b32 v252, s23, 23
	v_writelane_b32 v252, s24, 24
	v_writelane_b32 v252, s25, 25
	v_writelane_b32 v252, s26, 26
	v_writelane_b32 v252, s27, 27
	v_writelane_b32 v252, s28, 28
	v_writelane_b32 v252, s29, 29
	v_writelane_b32 v252, s30, 30
	v_writelane_b32 v252, s31, 31
	v_writelane_b32 v252, s32, 32
	v_writelane_b32 v252, s33, 33
	v_writelane_b32 v252, s34, 34
	v_writelane_b32 v252, s35, 35
	v_writelane_b32 v252, s36, 36
	v_writelane_b32 v252, s37, 37
	v_writelane_b32 v252, s38, 38
	v_writelane_b32 v252, s39, 39
	v_writelane_b32 v252, s40, 40
	v_writelane_b32 v252, s41, 41
	v_writelane_b32 v252, s42, 42
	v_writelane_b32 v252, s43, 43
	v_writelane_b32 v252, s44, 44
	v_writelane_b32 v252, s45, 45
	v_writelane_b32 v252, s46, 46
	v_writelane_b32 v252, s47, 47
	v_writelane_b32 v252, s48, 48
	v_writelane_b32 v252, s49, 49
	v_writelane_b32 v252, s50, 50
	v_writelane_b32 v252, s51, 51
	v_writelane_b32 v252, s52, 52
	v_writelane_b32 v252, s53, 53
	v_writelane_b32 v252, s54, 54
	v_writelane_b32 v252, s55, 55
	v_writelane_b32 v252, s56, 56
	v_writelane_b32 v252, s57, 57
	v_writelane_b32 v252, s58, 58
	v_writelane_b32 v252, s59, 59
	v_writelane_b32 v252, s60, 60
	v_writelane_b32 v252, s61, 61
	v_writelane_b32 v252, s62, 62
	v_writelane_b32 v252, s63, 63
	v_writelane_b32 v253, s64, 0
	v_writelane_b32 v253, s65, 1
	v_writelane_b32 v253, s66, 2
	v_writelane_b32 v253, s67, 3
	v_writelane_b32 v253, s68, 4
	v_writelane_b32 v253, s69, 5
	v_writelane_b32 v253, s70, 6
	v_writelane_b32 v253, s71, 7
	v_writelane_b32 v253, s72, 8
	v_writelane_b32 v253, s73, 9
	v_writelane_b32 v253, s74, 10
	v_writelane_b32 v253, s75, 11
	v_writelane_b32 v253, s76, 12
	v_writelane_b32 v253, s77, 13
	v_writelane_b32 v253, s78, 14
	v_writelane_b32 v253, s79, 15
	v_writelane_b32 v253, s80, 16
	v_writelane_b32 v253, s81, 17
	v_writelane_b32 v253, s82, 18
	v_writelane_b32 v253, s83, 19
	v_writelane_b32 v253, s84, 20
	v_writelane_b32 v253, s85, 21
	v_writelane_b32 v253, s86, 22
	v_writelane_b32 v253, s87, 23
	v_writelane_b32 v253, s88, 24
	v_writelane_b32 v253, s89, 25
	v_writelane_b32 v253, s90, 26
	v_writelane_b32 v253, s91, 27
	v_writelane_b32 v253, s92, 28
	v_writelane_b32 v253, s93, 29
	v_writelane_b32 v253, s94, 30
	v_writelane_b32 v253, s95, 31
	v_writelane_b32 v253, s96, 32
	v_writelane_b32 v253, s97, 33
	s_mov_b32 s100, 5
	s_mov_b32 s98, 0x89ff
	v_and_b32_e32 v237, 63, v178
	v_readlane_b32 s99, v255, 13
	v_readfirstlane_b32 s37, v178
	s_nop 4
	s_sub_i32 s101, s34, 172
	s_lshl_b32 s101, s101, 3
	s_add_i32 s99, s99, s101
	s_add_i32 s30, s99, 0x7400
	s_movk_i32 s86, 672
	s_branch .Lcv_hop_entry

; __global__ void __launch_bounds__(NTHREADS, 2) fwd_kernel(Params P) {
	.amdhsa_kernel _Z10fwd_kernel6Params
		.amdhsa_group_segment_fixed_size 0
		.amdhsa_private_segment_fixed_size 0
		.amdhsa_kernarg_size 552
		.amdhsa_user_sgpr_count 2
		.amdhsa_user_sgpr_dispatch_ptr 0
		.amdhsa_user_sgpr_queue_ptr 0
		.amdhsa_user_sgpr_kernarg_segment_ptr 1
		.amdhsa_user_sgpr_dispatch_id 0
		.amdhsa_user_sgpr_kernarg_preload_length 0
		.amdhsa_user_sgpr_kernarg_preload_offset 0
		.amdhsa_user_sgpr_private_segment_size 0
		.amdhsa_uses_dynamic_stack 0
		.amdhsa_enable_private_segment 0
		.amdhsa_system_sgpr_workgroup_id_x 1
		.amdhsa_system_sgpr_workgroup_id_y 0
		.amdhsa_system_sgpr_workgroup_id_z 0
		.amdhsa_system_sgpr_workgroup_info 0
		.amdhsa_system_vgpr_workitem_id 2
		.amdhsa_next_free_vgpr 256
		.amdhsa_next_free_sgpr 102
		.amdhsa_accum_offset 256
		.amdhsa_reserve_vcc 1
		.amdhsa_float_round_mode_32 0
		.amdhsa_float_round_mode_16_64 0
		.amdhsa_float_denorm_mode_32 3
		.amdhsa_float_denorm_mode_16_64 3
		.amdhsa_dx10_clamp 1
		.amdhsa_ieee_mode 1
		.amdhsa_fp16_overflow 0
		.amdhsa_tg_split 0
		.amdhsa_exception_fp_ieee_invalid_op 0
		.amdhsa_exception_fp_denorm_src 0
		.amdhsa_exception_fp_ieee_div_zero 0
		.amdhsa_exception_fp_ieee_overflow 0
		.amdhsa_exception_fp_ieee_underflow 0
		.amdhsa_exception_fp_ieee_inexact 0
		.amdhsa_exception_int_div_zero 0
	.end_amdhsa_kernel

; __global__ void __launch_bounds__(NTHREADS, 2) fwd_kernel(Params P) {
amdhsa.kernels:
  - .agpr_count:     0
    .args:
      - .offset:         0
        .size:           296
        .value_kind:     by_value
      - .offset:         296
        .size:           4
        .value_kind:     hidden_block_count_x
      - .offset:         300
        .size:           4
        .value_kind:     hidden_block_count_y
      - .offset:         304
        .size:           4
        .value_kind:     hidden_block_count_z
      - .offset:         308
        .size:           2
        .value_kind:     hidden_group_size_x
      - .offset:         310
        .size:           2
        .value_kind:     hidden_group_size_y
      - .offset:         312
        .size:           2
        .value_kind:     hidden_group_size_z
      - .offset:         314
        .size:           2
        .value_kind:     hidden_remainder_x
      - .offset:         316
        .size:           2
        .value_kind:     hidden_remainder_y
      - .offset:         318
        .size:           2
        .value_kind:     hidden_remainder_z
      - .offset:         336
        .size:           8
        .value_kind:     hidden_global_offset_x
      - .offset:         344
        .size:           8
        .value_kind:     hidden_global_offset_y
      - .offset:         352
        .size:           8
        .value_kind:     hidden_global_offset_z
      - .offset:         360
        .size:           2
        .value_kind:     hidden_grid_dims
      - .offset:         384
        .size:           8
        .value_kind:     hidden_multigrid_sync_arg
      - .offset:         416
        .size:           4
        .value_kind:     hidden_dynamic_lds_size
    .group_segment_fixed_size: 0
    .kernarg_segment_align: 8
    .kernarg_segment_size: 552
    .language:       OpenCL C
    .language_version:
      - 2
      - 0
    .max_flat_workgroup_size: 512
    .name:           _Z10fwd_kernel6Params
    .private_segment_fixed_size: 0
    .sgpr_count:     108
    .sgpr_spill_count: 99
    .symbol:         _Z10fwd_kernel6Params.kd
    .uniform_work_group_size: 1
    .uses_dynamic_stack: false
    .vgpr_count:     256
    .vgpr_spill_count: 0
    .wavefront_size: 64
